# attention K-tile LDS swizzle uses 4 row bits (conflict-free ds_read_b128) instead of 3
# speedup vs baseline: 1.0044x; 1.0044x over previous
; __device__ __forceinline__ int v_st(int k, int c) { const int kk = (k & ~0xC) | ((k & 4) << 1) | ((k & 8) >> 1); return ((kk >> 3) * 4 + (c >> 5)) * 512 + ((kk & 7) * 32 + (c & 31)) * 2; }
; __device__ __forceinline__ int v_rd_base(int lane) { return ((lane & 3) << 3) | (((lane >> 2) & 3) << 6) | (((lane >> 4) & 1) << 5) | (((lane >> 5) & 1) << 8); }
; __device__ __forceinline__ void qkt(f32x16& p0, f32x16& p1, const bf16* Ks, const bf16x8* qr, int r32, int hi) {
;   p0 = f32x16{}; p1 = f32x16{};
;   for (int d0 = 0; d0 < 8; ++d0) { int cb = (d0 * 16 + hi * 8) * 2;
;     bf16x8 b0 = *reinterpret_cast<const bf16x8*>((const char*)Ks + KSWZ(r32, cb));
;     bf16x8 b1 = *reinterpret_cast<const bf16x8*>((const char*)Ks + KSWZ(32 + r32, cb));
;     p0 = __builtin_amdgcn_mfma_f32_32x32x16_bf16(b0, qr[d0], p0, 0, 0, 0);
;     p1 = __builtin_amdgcn_mfma_f32_32x32x16_bf16(b1, qr[d0], p1, 0, 0, 0); }
; template <typename TQ>
; __device__ __forceinline__ void attn_dense_body(const TQ* __restrict__ Qb, const bf16* __restrict__ Kh, const bf16* __restrict__ Vh,
;                                                 bf16* __restrict__ Ob, int seq, char* lds, const int tid) {
;     ...
;   const int wid = __builtin_amdgcn_readfirstlane(tid >> 6), lane = tid & 63, r32 = lane & 31, hi = lane >> 5;
;   bf16* V_lds = (bf16*)lds; bf16* K_lds = (bf16*)(lds + 2 * SHM_V);
;   float* ws = (float*)(lds + 2 * SHM_V + 2 * SHM_K) + wid * 64; float* li_l = ws; float* al_l = ws + 32;
;   float m_reg = -1e30f, l_reg = 0; f32x16 o[4] = {}; bf16x8 qr[8];
;   const TQ* Qw = Qb + (long)(wid * QBLK + r32) * LDQ + hi * 8;
; #pragma unroll
;   for (int d0 = 0; d0 < 8; ++d0) qr[d0] = SQ::tobf(SQ::ld8(Qw + d0 * 16));
;   const int sr = tid >> 4, sc = (tid & 15) * 8, vst0 = v_st(sr, sc), vst1 = v_st(32 + sr, sc);
;   const int vb0 = (int)(uintptr_t)V_lds + v_rd_base(lane);
;   struct { typename St::T vs0, vs1, ks0, ks1; } sr_[SDEPTH];
;     ...
;   f32x16 pA0, pA1, pB0, pB1; float mnA, mnB, alA, alB; bf16x8 pa0, pa1, pa2, pa3; const int NT = seq / KVBLK;
;   constexpr int SE = 0, SO = SDEPTH - 1;
;   SLOAD(SE, 0); asm volatile("s_waitcnt vmcnt(0)" ::: "memory"); SWRITE(0, SE); __syncthreads();
;   qkt(pA0, pA1, K_lds, qr, r32, hi); partialSM(pA0, pA1, m_reg, mnA, alA);
.LBB0_1528:
	s_lshr_b32 s5, s2, 4
	s_ashr_i32 s4, s2, 7
	s_bfe_u32 s16, s5, 0x10002
	s_ashr_i32 s5, s4, 31
	s_lshl_b64 s[6:7], s[4:5], 12
	s_lshl_b32 s5, s2, 8
	s_and_b32 s5, s5, 0xf00
	s_bfe_u32 s8, s2, 0x30004
	s_or_b32 s5, s6, s5
	s_add_u32 s18, s5, 0x800
	s_addc_u32 s19, s7, 0
	s_mul_i32 s5, s19, 0xc00
	s_mul_hi_u32 s6, s18, 0xc00
	s_add_i32 s6, s6, s5
	s_mul_i32 s5, s18, 0xc00
	s_add_u32 s5, s24, s5
	s_addc_u32 s6, s25, s6
	s_lshl_b32 s15, s8, 7
	s_lshl_b32 s7, s8, 8
	s_add_u32 s8, s5, s7
	s_addc_u32 s9, s6, 0
	s_lshl_b32 s4, s4, 1
	v_mbcnt_lo_u32_b32 v0, -1, 0
	v_mbcnt_hi_u32_b32 v0, -1, v0
	s_or_b32 s16, s16, s4
	v_add_u32_e32 v52, s74, v0
	s_mul_i32 s6, s16, 0x110000
	v_readlane_b32 s4, v254, 14
	v_ashrrev_i32_e32 v16, 4, v52
	s_mul_hi_i32 s7, s16, 0x110000
	v_readlane_b32 s5, v254, 15
	s_add_u32 s4, s4, s6
	v_lshlrev_b32_e32 v22, 3, v52
	v_add_u32_e32 v18, 32, v16
	s_addc_u32 s5, s5, s7
	v_and_b32_e32 v0, 0x78, v22
	v_ashrrev_i32_e32 v17, 31, v16
	v_ashrrev_i32_e32 v19, 31, v18
	s_add_u32 s6, s3, s6
	v_lshlrev_b32_e32 v23, 1, v0
	v_lshlrev_b64 v[48:49], 8, v[16:17]
	s_waitcnt vmcnt(8)
	v_lshlrev_b64 v[12:13], 8, v[18:19]
	s_addc_u32 s7, s11, s7
	v_or_b32_e32 v50, v48, v23
	v_mov_b32_e32 v51, v49
	v_or_b32_e32 v12, v12, v23
	v_lshl_add_u64 v[0:1], s[6:7], 0, v[50:51]
	v_lshl_add_u64 v[4:5], s[6:7], 0, v[12:13]
	s_barrier
	global_load_dwordx4 v[0:3], v[0:1], off
	s_nop 0
	global_load_dwordx4 v[4:7], v[4:5], off
	v_lshl_add_u64 v[8:9], s[4:5], 0, v[50:51]
	global_load_dwordx4 v[8:11], v[8:9], off
	v_lshl_add_u64 v[12:13], s[4:5], 0, v[12:13]
	v_readfirstlane_b32 s17, v52
	global_load_dwordx4 v[12:15], v[12:13], off
	s_ashr_i32 s20, s17, 1
	v_mov_b32_e32 v17, s20
	s_movk_i32 s21, 0xffe0
	v_bfe_u32 v182, v52, 5, 1
	v_bfi_b32 v17, s21, v17, v52
	v_mov_b64_e32 v[20:21], s[8:9]
	s_movk_i32 s8, 0xc00
	v_mad_i64_i32 v[20:21], s[8:9], v17, s8, v[20:21]
	v_lshlrev_b32_e32 v176, 4, v182
	v_lshl_add_u64 v[20:21], v[20:21], 0, v[176:177]
	global_load_dwordx4 v[120:123], v[20:21], off
	global_load_dwordx4 v[112:115], v[20:21], off offset:32
	global_load_dwordx4 v[124:127], v[20:21], off offset:64
	global_load_dwordx4 v[116:119], v[20:21], off offset:96
	global_load_dwordx4 v[108:111], v[20:21], off offset:128
	global_load_dwordx4 v[104:107], v[20:21], off offset:160
	global_load_dwordx4 v[100:103], v[20:21], off offset:192
	global_load_dwordx4 v[96:99], v[20:21], off offset:224
	v_and_b32_e32 v17, 0xfffff0, v16
	v_lshlrev_b32_e32 v19, 1, v16
	v_lshrrev_b32_e32 v24, 1, v16
	v_and_b32_e32 v25, 3, v16
	v_and_or_b32 v17, v19, 8, v17
	v_and_or_b32 v19, v24, 4, v25
	v_and_b32_e32 v24, 0xfffff0, v18
	v_lshlrev_b32_e32 v25, 1, v18
	v_bfe_u32 v22, v22, 5, 2
	v_lshrrev_b32_e32 v17, 1, v17
	v_and_or_b32 v24, v25, 8, v24
	v_or_b32_e32 v17, v17, v22
	v_lshrrev_b32_e32 v24, 1, v24
	v_lshlrev_b32_e32 v19, 6, v19
	v_and_b32_e32 v26, 48, v23
	v_lshlrev_b32_e32 v17, 9, v17
	v_or_b32_e32 v22, v24, v22
	v_or3_b32 v17, v17, v19, v26
	v_lshlrev_b32_e32 v22, 9, v22
	v_or3_b32 v19, v22, v19, v26
	v_add_u32_e32 v188, 0, v17
	v_add_u32_e32 v189, 0, v19
	s_waitcnt vmcnt(0)
	v_and_b32_e32 v183, 31, v52
	v_lshlrev_b32_e32 v53, 4, v52
	v_and_b32_e32 v76, 63, v52
	s_mov_b64 s[36:37], 0x4000
	v_lshl_add_u64 v[62:63], v[50:51], 0, s[36:37]
	s_mov_b64 s[36:37], 0x6000
	s_waitcnt vmcnt(11)
	ds_write_b128 v188, v[0:3]
	s_waitcnt vmcnt(10)
	ds_write_b128 v189, v[4:7]
	v_lshlrev_b32_e32 v0, 8, v16
	v_and_b32_e32 v1, 0xf0, v52
	v_bitop3_b32 v0, v23, v0, v1 bitop3:0xde
	v_add_u32_e32 v190, 0, v0
	v_lshlrev_b32_e32 v0, 8, v18
	s_waitcnt vmcnt(9)
	ds_write_b128 v190, v[8:11] offset:32768
	v_bitop3_b32 v0, v23, v0, v1 bitop3:0xde
	v_lshlrev_b32_e32 v8, 8, v183
	v_and_b32_e32 v9, 0xf0, v53
	v_add_u32_e32 v191, 0, v0
	v_bitop3_b32 v0, v176, v8, v9 bitop3:0xde
	v_add_u32_e32 v192, 0, v0
	s_waitcnt vmcnt(8)
	ds_write_b128 v191, v[12:15] offset:32768
	s_waitcnt lgkmcnt(0)
	s_barrier
	ds_read_b128 v[0:3], v192 offset:32768
	ds_read_b128 v[4:7], v192 offset:40960
	s_waitcnt vmcnt(7) lgkmcnt(1)
	v_mfma_f32_32x32x16_bf16 v[32:47], v[0:3], v[120:123], 0
	v_or_b32_e32 v0, 32, v176
	v_bitop3_b32 v0, v0, v8, v9 bitop3:0xde
	v_add_u32_e32 v199, 0, v0
	v_lshlrev_b32_e32 v10, 3, v76
	v_lshlrev_b32_e32 v12, 1, v52
	v_lshl_add_u64 v[64:65], v[50:51], 0, s[36:37]
	v_lshl_add_u64 v[58:59], s[6:7], 0, v[64:65]
	s_waitcnt lgkmcnt(0)
	v_mfma_f32_32x32x16_bf16 v[16:31], v[4:7], v[120:123], 0
	ds_read_b128 v[0:3], v199 offset:32768
	ds_read_b128 v[4:7], v199 offset:40960
	v_lshl_add_u64 v[66:67], s[4:5], 0, v[64:65]
	s_mov_b64 s[36:37], 0xa000
	s_and_b32 s8, s17, 0x3fffffc0
	s_lshl_b32 s8, s8, 2
	s_add_i32 s8, s8, 0
	s_add_i32 s8, s8, 0x10000
	s_waitcnt vmcnt(6) lgkmcnt(1)
	v_mfma_f32_32x32x16_bf16 v[32:47], v[0:3], v[112:115], v[32:47]
	v_or_b32_e32 v0, 64, v176
	v_bitop3_b32 v0, v0, v8, v9 bitop3:0xde
	v_add_u32_e32 v198, 0, v0
	s_andn2_b32 s20, s20, 31
	s_cmp_lg_u32 0, -1
	s_cselect_b32 s9, 0, 0
	s_mov_b32 s57, s56
	s_waitcnt lgkmcnt(0)
	v_mfma_f32_32x32x16_bf16 v[16:31], v[4:7], v[112:115], v[16:31]
	ds_read_b128 v[0:3], v198 offset:32768
	ds_read_b128 v[4:7], v198 offset:40960
	s_mov_b32 s58, s56
	s_mov_b32 s59, s56
	s_mov_b32 s60, s56
	s_mov_b32 s61, s56
	s_mov_b32 s62, s56
	s_mov_b32 s63, s56
	s_waitcnt vmcnt(5) lgkmcnt(1)
	v_mfma_f32_32x32x16_bf16 v[32:47], v[0:3], v[124:127], v[32:47]
	v_or_b32_e32 v0, 0x60, v176
	v_bitop3_b32 v0, v0, v8, v9 bitop3:0xde
	v_add_u32_e32 v195, 0, v0
	s_mov_b32 s64, s56
	s_mov_b32 s65, s56
	s_mov_b32 s66, s56
	s_mov_b32 s67, s56
	s_waitcnt lgkmcnt(0)
; __device__ __forceinline__ int v_st(int k, int c) { const int kk = (k & ~0xC) | ((k & 4) << 1) | ((k & 8) >> 1); return ((kk >> 3) * 4 + (c >> 5)) * 512 + ((kk & 7) * 32 + (c & 31)) * 2; }
; __device__ __forceinline__ int v_rd_base(int lane) { return ((lane & 3) << 3) | (((lane >> 2) & 3) << 6) | (((lane >> 4) & 1) << 5) | (((lane >> 5) & 1) << 8); }
; __device__ __forceinline__ void qkt(f32x16& p0, f32x16& p1, const bf16* Ks, const bf16x8* qr, int r32, int hi) {
;   p0 = f32x16{}; p1 = f32x16{};
;   for (int d0 = 0; d0 < 8; ++d0) { int cb = (d0 * 16 + hi * 8) * 2;
;     bf16x8 b0 = *reinterpret_cast<const bf16x8*>((const char*)Ks + KSWZ(r32, cb));
;     bf16x8 b1 = *reinterpret_cast<const bf16x8*>((const char*)Ks + KSWZ(32 + r32, cb));
;     p0 = __builtin_amdgcn_mfma_f32_32x32x16_bf16(b0, qr[d0], p0, 0, 0, 0);
;     p1 = __builtin_amdgcn_mfma_f32_32x32x16_bf16(b1, qr[d0], p1, 0, 0, 0); }
; }
; template <typename TQ>
; __device__ __forceinline__ void attn_dense_body(const TQ* __restrict__ Qb, const bf16* __restrict__ Kh, const bf16* __restrict__ Vh,
;                                                 bf16* __restrict__ Ob, int seq, char* lds, const int tid) {
;     ...
;   const int sr = tid >> 4, sc = (tid & 15) * 8, vst0 = v_st(sr, sc), vst1 = v_st(32 + sr, sc);
;   const int vb0 = (int)(uintptr_t)V_lds + v_rd_base(lane);
	v_mfma_f32_32x32x16_bf16 v[16:31], v[4:7], v[124:127], v[16:31]
	ds_read_b128 v[0:3], v195 offset:32768
	ds_read_b128 v[4:7], v195 offset:40960
	s_mov_b32 s68, s56
	s_mov_b32 s69, s56
	s_mov_b32 s70, s56
	s_mov_b32 s71, s56
	v_lshl_add_u32 v184, v183, 2, s8
	v_mov_b32_e32 v185, 0
	s_waitcnt vmcnt(4) lgkmcnt(1)
	v_mfma_f32_32x32x16_bf16 v[32:47], v[0:3], v[116:119], v[32:47]
	v_or_b32_e32 v0, 0x80, v176
	v_bitop3_b32 v0, v0, v8, v9 bitop3:0xde
	v_add_u32_e32 v194, 0, v0
	s_waitcnt lgkmcnt(0)
	v_mfma_f32_32x32x16_bf16 v[16:31], v[4:7], v[116:119], v[16:31]
	ds_read_b128 v[0:3], v194 offset:32768
	ds_read_b128 v[4:7], v194 offset:40960
	s_waitcnt vmcnt(3) lgkmcnt(1)
	v_mfma_f32_32x32x16_bf16 v[32:47], v[0:3], v[108:111], v[32:47]
	v_or_b32_e32 v0, 0xa0, v176
	v_bitop3_b32 v0, v0, v8, v9 bitop3:0xde
	v_add_u32_e32 v193, 0, v0
	ds_read_b128 v[0:3], v193 offset:32768
	s_waitcnt lgkmcnt(1)
	v_mfma_f32_32x32x16_bf16 v[16:31], v[4:7], v[108:111], v[16:31]
	ds_read_b128 v[4:7], v193 offset:40960
	s_waitcnt vmcnt(2) lgkmcnt(1)
	v_mfma_f32_32x32x16_bf16 v[32:47], v[0:3], v[104:107], v[32:47]
	v_and_b32_e32 v0, 0xc0, v53
	v_and_or_b32 v11, v10, 24, v0
	v_or_b32_e32 v0, 0xc0, v176
	v_bitop3_b32 v0, v0, v8, v9 bitop3:0xde
	v_add_u32_e32 v196, 0, v0
	ds_read_b128 v[0:3], v196 offset:32768
	s_waitcnt lgkmcnt(1)
	v_mfma_f32_32x32x16_bf16 v[16:31], v[4:7], v[104:107], v[16:31]
	v_and_b32_e32 v4, 32, v12
	v_and_b32_e32 v5, 0x100, v10
	v_or3_b32 v53, v11, v4, v5
	ds_read_b128 v[4:7], v196 offset:40960
	v_add_u32_e32 v187, s9, v53
	s_waitcnt vmcnt(1) lgkmcnt(1)
	v_mfma_f32_32x32x16_bf16 v[32:47], v[0:3], v[100:103], v[32:47]
	v_or_b32_e32 v0, 0xe0, v176
	v_bitop3_b32 v0, v0, v8, v9 bitop3:0xde
	v_add_u32_e32 v197, 0, v0
	ds_read_b128 v[0:3], v197 offset:32768
	ds_read_b128 v[54:57], v197 offset:40960
	s_waitcnt lgkmcnt(2)
	v_mfma_f32_32x32x16_bf16 v[16:31], v[4:7], v[100:103], v[16:31]
	s_waitcnt vmcnt(0) lgkmcnt(1)
	v_mfma_f32_32x32x16_bf16 v[32:47], v[0:3], v[96:99], v[32:47]
	v_mov_b64_e32 v[0:1], s[56:57]
	v_mov_b64_e32 v[14:15], s[70:71]
	v_mov_b64_e32 v[2:3], s[58:59]
	v_mov_b64_e32 v[4:5], s[60:61]
	v_mov_b64_e32 v[6:7], s[62:63]
	v_mov_b64_e32 v[8:9], s[64:65]
	v_mov_b64_e32 v[10:11], s[66:67]
	s_waitcnt lgkmcnt(0)
; #define SLOAD(i, k0) do { sr_[i].vs0 = St::ld8(&Vh[(long)((k0) + sr) * LDK + sc]); sr_[i].vs1 = St::ld8(&Vh[(long)((k0) + 32 + sr) * LDK + sc]); \
;     sr_[i].ks0 = St::ld8(&Kh[(long)((k0) + sr) * LDK + sc]); sr_[i].ks1 = St::ld8(&Kh[(long)((k0) + 32 + sr) * LDK + sc]); } while (0)
; #define SWAIT() do { if constexpr (SDEPTH == 2) asm volatile("s_waitcnt vmcnt(4)" ::: "memory"); else asm volatile("s_waitcnt vmcnt(0)" ::: "memory"); } while (0)
; __device__ __forceinline__ void partialSM(f32x16& p0, f32x16& p1, float& m_reg, float& mn, float& alpha) {
;   constexpr float C = SCALE * 1.4426950408889634f;
;   float pmax = p0[0]; for (int r = 1; r < 16; ++r) pmax = fmaxf(pmax, p0[r]); for (int r = 0; r < 16; ++r) pmax = fmaxf(pmax, p1[r]);
;   { auto rr = __builtin_amdgcn_permlane32_swap(__float_as_uint(pmax), __float_as_uint(pmax), false, false);
;     pmax = fmaxf(__uint_as_float(rr[0]), __uint_as_float(rr[1])); }
;   if (__builtin_expect(__all(pmax - m_reg <= THR / SCALE), 1)) { mn = m_reg; alpha = 1.f; }
;   else { mn = fmaxf(m_reg, pmax); alpha = __builtin_amdgcn_exp2f((m_reg - mn) * C); m_reg = mn; }
;   float mnC = -mn * C;
;   for (int r = 0; r < 16; ++r) p0[r] = fmaf(p0[r], C, mnC); for (int r = 0; r < 16; ++r) p1[r] = fmaf(p1[r], C, mnC);
;   for (int r = 0; r < 16; ++r) p0[r] = __builtin_amdgcn_exp2f(p0[r]);
; template <typename TQ>
; __device__ __forceinline__ void attn_dense_body(const TQ* __restrict__ Qb, const bf16* __restrict__ Kh, const bf16* __restrict__ Vh,
;                                                 bf16* __restrict__ Ob, int seq, char* lds, const int tid) {
;     ...
;   qkt(pA0, pA1, K_lds, qr, r32, hi); partialSM(pA0, pA1, m_reg, mnA, alA);
;   SLOAD(SO, KVBLK); if constexpr (SDEPTH == 2) { if (2 < NT) SLOAD(SE, 2 * KVBLK); }
;   SWAIT(); SWRITE(1, SO); __syncthreads();
	v_mfma_f32_32x32x16_bf16 v[16:31], v[54:57], v[96:99], v[16:31]
	s_nop 2
	v_max_f32_e32 v54, v33, v33
	v_max_f32_e32 v55, v32, v32
	v_max_f32_e32 v54, v55, v54
	v_max3_f32 v54, v54, v34, v35
	v_max3_f32 v54, v54, v36, v37
	v_max3_f32 v54, v54, v38, v39
	v_max3_f32 v54, v54, v40, v41
	v_max3_f32 v54, v54, v42, v43
	v_max3_f32 v54, v54, v44, v45
	v_max3_f32 v54, v54, v46, v47
	v_max3_f32 v70, v54, v16, v17
	v_max3_f32 v70, v70, v18, v19
	v_max3_f32 v70, v70, v20, v21
	v_max3_f32 v70, v70, v22, v23
	v_max3_f32 v70, v70, v24, v25
	v_max3_f32 v70, v70, v26, v27
	v_lshl_add_u64 v[54:55], s[6:7], 0, v[62:63]
	v_lshl_add_u64 v[62:63], s[4:5], 0, v[62:63]
	v_max3_f32 v70, v70, v28, v29
	global_load_dwordx4 v[54:57], v[54:55], off
	s_nop 0
	global_load_dwordx4 v[58:61], v[58:59], off
	s_nop 0
	global_load_dwordx4 v[62:65], v[62:63], off
	s_nop 0
	global_load_dwordx4 v[66:69], v[66:67], off
	v_max3_f32 v77, v70, v30, v31
	v_lshl_add_u64 v[70:71], v[50:51], 0, s[12:13]
	v_lshl_add_u64 v[72:73], s[6:7], 0, v[70:71]
	v_lshl_add_u64 v[50:51], v[50:51], 0, s[36:37]
	v_lshl_add_u64 v[70:71], s[4:5], 0, v[70:71]
	v_lshl_add_u64 v[74:75], s[6:7], 0, v[50:51]
	global_load_dwordx4 v[128:131], v[72:73], off
	global_load_dwordx4 v[136:139], v[74:75], off
	v_lshl_add_u64 v[50:51], s[4:5], 0, v[50:51]
	global_load_dwordx4 v[132:135], v[70:71], off
	global_load_dwordx4 v[140:143], v[50:51], off
	v_mov_b32_e32 v78, v77
	s_nop 1
	v_permlane32_swap_b32_e32 v77, v78
	v_max_f32_e32 v50, v78, v78
	v_max_f32_e32 v51, v77, v77
	v_max_f32_e32 v50, v51, v50
	v_add_f32_e32 v51, 0x7149f2ca, v50
	v_max_f32_e32 v50, 0xf149f2ca, v50
	v_cmp_ge_f32_e32 vcc, s14, v51
	v_sub_f32_e32 v51, 0xf149f2ca, v50
	v_mul_f32_e32 v51, 0x3e0293ee, v51
	v_exp_f32_e32 v51, v51
	s_cmp_eq_u64 vcc, exec
	s_cselect_b64 vcc, -1, 0
	v_cndmask_b32_e32 v164, v50, v180, vcc
	v_mul_f32_e32 v50, 0xbe0293ee, v164
	v_cndmask_b32_e64 v200, v51, 1.0, vcc
	v_mov_b32_e32 v51, v50
	v_fmamk_f32 v32, v32, 0x3e0293ee, v50
	v_fmamk_f32 v33, v33, 0x3e0293ee, v50
	v_fmamk_f32 v34, v34, 0x3e0293ee, v50
	v_fmamk_f32 v35, v35, 0x3e0293ee, v50
	v_fmamk_f32 v36, v36, 0x3e0293ee, v50
	v_fmamk_f32 v37, v37, 0x3e0293ee, v50
	v_fmamk_f32 v38, v38, 0x3e0293ee, v50
	v_fmamk_f32 v39, v39, 0x3e0293ee, v50
	v_fmamk_f32 v40, v40, 0x3e0293ee, v50
	v_fmamk_f32 v41, v41, 0x3e0293ee, v50
	v_fmamk_f32 v42, v42, 0x3e0293ee, v50
	v_fmamk_f32 v43, v43, 0x3e0293ee, v50
	v_fmamk_f32 v44, v44, 0x3e0293ee, v50
	v_fmamk_f32 v45, v45, 0x3e0293ee, v50
	v_fmamk_f32 v46, v46, 0x3e0293ee, v50
	v_fmac_f32_e32 v51, 0x3e0293ee, v47
	v_pk_fma_f32 v[154:155], v[18:19], s[10:11], v[50:51] op_sel_hi:[1,0,0]
	v_pk_fma_f32 v[156:157], v[16:17], s[10:11], v[50:51] op_sel_hi:[1,0,0]
	v_exp_f32_e32 v161, v32
	v_exp_f32_e32 v162, v33
	v_exp_f32_e32 v174, v34
	v_exp_f32_e32 v175, v35
	v_exp_f32_e32 v204, v36
	v_exp_f32_e32 v207, v37
	v_exp_f32_e32 v163, v38
	v_exp_f32_e32 v173, v39
	v_exp_f32_e32 v168, v40
	v_exp_f32_e32 v170, v41
	v_exp_f32_e32 v171, v42
	v_exp_f32_e32 v172, v43
	v_exp_f32_e32 v165, v44
	v_exp_f32_e32 v166, v45
	v_exp_f32_e32 v167, v46
	v_exp_f32_e32 v169, v51
	v_mad_i64_i32 v[16:17], s[4:5], s16, v181, v[48:49]
	v_and_b32_e32 v18, 15, v52
	s_waitcnt vmcnt(4)
	s_addk_i32 s9, 0x4000
	v_lshl_or_b32 v16, v18, 4, v16
	v_mov_b64_e32 v[12:13], s[68:69]
	v_pk_fma_f32 v[150:151], v[30:31], s[10:11], v[50:51] op_sel_hi:[1,0,0]
	v_pk_fma_f32 v[152:153], v[28:29], s[10:11], v[50:51] op_sel_hi:[1,0,0]
	v_pk_fma_f32 v[158:159], v[26:27], s[10:11], v[50:51] op_sel_hi:[1,0,0]
	v_pk_fma_f32 v[144:145], v[24:25], s[10:11], v[50:51] op_sel_hi:[1,0,0]
	v_pk_fma_f32 v[146:147], v[22:23], s[10:11], v[50:51] op_sel_hi:[1,0,0]
	v_pk_fma_f32 v[148:149], v[20:21], s[10:11], v[50:51] op_sel_hi:[1,0,0]
	s_waitcnt vmcnt(7)
	ds_write_b128 v188, v[54:57] offset:16384
	s_waitcnt vmcnt(6)
	ds_write_b128 v189, v[58:61] offset:16384
	s_waitcnt vmcnt(5)
	ds_write_b128 v190, v[62:65] offset:49152
	s_waitcnt vmcnt(4)
	ds_write_b128 v191, v[66:69] offset:49152
	v_add_u32_e32 v186, s9, v53
	v_lshl_add_u64 v[178:179], s[0:1], 0, v[16:17]
	v_mov_b64_e32 v[62:63], v[14:15]
	v_mov_b64_e32 v[46:47], v[14:15]
	v_mov_b64_e32 v[30:31], v[14:15]
	v_cmp_gt_u32_e64 s[36:37], 32, v76
	v_mov_b64_e32 v[60:61], v[12:13]
	v_mov_b64_e32 v[58:59], v[10:11]
	v_mov_b64_e32 v[56:57], v[8:9]
	v_mov_b64_e32 v[54:55], v[6:7]
	v_mov_b64_e32 v[52:53], v[4:5]
	v_mov_b64_e32 v[50:51], v[2:3]
	v_mov_b64_e32 v[48:49], v[0:1]
	v_mov_b64_e32 v[44:45], v[12:13]
	v_mov_b64_e32 v[42:43], v[10:11]
	v_mov_b64_e32 v[40:41], v[8:9]
	v_mov_b64_e32 v[38:39], v[6:7]
	v_mov_b64_e32 v[36:37], v[4:5]
	v_mov_b64_e32 v[34:35], v[2:3]
	v_mov_b64_e32 v[32:33], v[0:1]
	v_mov_b64_e32 v[28:29], v[12:13]
	v_mov_b64_e32 v[26:27], v[10:11]
	v_mov_b64_e32 v[24:25], v[8:9]
	v_mov_b64_e32 v[22:23], v[6:7]
	v_mov_b64_e32 v[20:21], v[4:5]
	v_mov_b64_e32 v[18:19], v[2:3]
	v_mov_b64_e32 v[16:17], v[0:1]
	s_mov_b32 s9, 1
	s_waitcnt lgkmcnt(0)
	s_barrier
